# v6 + hand-written EPI phase: DPP/permlane reductions instead of ds_bpermute, all row loads hoisted, one-row-ahead prefetch
# speedup vs baseline: 1.0449x; 1.0101x over previous
; __device__ __forceinline__ float lo2f(unsigned w) { return __uint_as_float(w << 16); }
; __device__ __forceinline__ float hi2f(unsigned w) { return __uint_as_float(w & 0xffff0000u); }
; __device__ __forceinline__ float siluf_(float x) { return x * __builtin_amdgcn_rcpf(1.f + __expf(-x)); }
; __device__ __forceinline__ int tidx() { int t = threadIdx.x & 255; asm volatile("" : "+v"(t)); return t; }
; __device__ __forceinline__ int bidx() { int t = blockIdx.x + half_id() * gridDim.x; asm volatile("" : "+s"(t)); return t; }
; __device__ __forceinline__ void epi_phase(CP p, int l) {
;   const int tid_ = tidx(); const int lane = tid_ & 63, gw = bidx() * 4 + (tid_ >> 6), nw = nvb() * 4;
;   const bf16_t* proj = (const bf16_t*)(p.ws + WS_PROJ);
;   const bf16_t* RW = (const bf16_t*)(p.ws + WS_RW);
;   const bf16_t* RG = (const bf16_t*)(p.ws + WS_RG);
;   const float* RC = (const float*)(p.ws + WS_RC);
;   bf16_t* Y = (bf16_t*)(p.ws + WS_Y);
;   const int c = lane * 4;
;   const float4 nw4 = *reinterpret_cast<const float4*>(p.in[13] + l * 256 + c);
;   const float4 lw4 = *reinterpret_cast<const float4*>(p.in[23] + l * 256 + c);
;   const float4 lb4 = *reinterpret_cast<const float4*>(p.in[24] + l * 256 + c);
;   for (int row = gw; row < R; row += nw) {
;     {
;       const uint2 yr = *reinterpret_cast<const uint2*>(Y + (size_t)row * 1024 + c);
;       const uint2 zr = *reinterpret_cast<const uint2*>(proj + (size_t)row * PJ + OFF_Z + c);
;       const float y0 = lo2f(yr.x) * siluf_(lo2f(zr.x)), y1 = hi2f(yr.x) * siluf_(hi2f(zr.x));
;       const float y2 = lo2f(yr.y) * siluf_(lo2f(zr.y)), y3 = hi2f(yr.y) * siluf_(hi2f(zr.y));
;       float ss = y0 * y0 + y1 * y1 + y2 * y2 + y3 * y3;
.LBB0_384:
	s_andn2_b64 vcc, exec, s[2:3]
	s_cbranch_vccnz .LBB0_1325
	s_lshl_b32 s1, s88, 2
	s_mov_b32 s0, s88
	s_lshl_b32 s74, s88, 8
	v_writelane_b32 v254, s1, 11
	s_ashr_i32 s1, s88, 31
	s_ashr_i32 s75, s74, 31
	v_writelane_b32 v254, s0, 12
	s_lshl_b32 s63, s14, 16
	s_cmp_lt_i32 s55, 3
	v_writelane_b32 v254, s1, 13
	s_mov_b64 s[2:3], -1
	s_cbranch_scc1 .LBB0_650
	s_cmp_gt_i32 s55, 3
	s_cbranch_scc0 .LBB0_391
	s_waitcnt vmcnt(0)
	v_readlane_b32 s34, v253, 63
	v_readlane_b32 s35, v254, 0
	s_nop 0
	s_load_dwordx2 s[4:5], s[34:35], 0x68
	s_load_dwordx4 s[12:15], s[34:35], 0xb8
	s_load_dwordx2 s[8:9], s[34:35], 0x100
	s_lshl_b64 s[10:11], s[74:75], 2
	v_lshlrev_b32_e32 v20, 3, v217
	v_add_u32_e32 v22, 0x1808, v20
	v_lshrrev_b32_e32 v23, 4, v217
	v_lshlrev_b32_e32 v23, 2, v23
	v_and_b32_e32 v21, 15, v217
	v_lshrrev_b32_e32 v84, 5, v217
	v_lshl_or_b32 v21, v84, 4, v21
	v_lshlrev_b32_e32 v21, 3, v21
	v_bfe_u32 v84, v217, 4, 1
	v_lshl_or_b32 v21, v84, 8, v21
	v_lshlrev_b32_e32 v85, 1, v21
	v_lshlrev_b32_e32 v86, 1, v20
	s_waitcnt lgkmcnt(0)
	s_add_u32 s4, s4, s10
	s_addc_u32 s5, s5, s11
	s_add_u32 s12, s12, s10
	s_addc_u32 s13, s13, s11
	s_add_u32 s14, s14, s10
	s_addc_u32 s15, s15, s11
	s_add_u32 s8, s8, s10
	s_addc_u32 s9, s9, s11
	global_load_dwordx4 v[24:27], v85, s[4:5]
	global_load_dwordx4 v[28:31], v86, s[12:13]
	global_load_dwordx4 v[32:35], v86, s[14:15]
	global_load_dwordx4 v[36:39], v86, s[8:9]
	v_readfirstlane_b32 s0, v213
	v_lshrrev_b32_e32 v84, 6, v214
	s_mul_i32 s0, s0, s46
	s_add_i32 s0, s0, s89
	v_readfirstlane_b32 s1, v84
	s_lshl_b32 s0, s0, 2
	s_add_i32 s0, s0, s1
	s_lshl_b32 s1, s46, 3
	s_lshl_b32 s28, s1, 11
	s_mul_i32 s29, s1, 0x1a10
	s_mul_i32 s30, s1, 0xc00
	s_lshl_b32 s31, s1, 9
	s_lshl_b32 s38, s1, 4
	s_lshl_b32 s2, s0, 11
	s_add_i32 s2, s2, 0x7a90800
	v_add_u32_e32 v72, s2, v21
	v_add_u32_e32 v73, s2, v20
	s_mul_i32 s2, s0, 0x1a10
	s_add_i32 s2, s2, 0x1180000
	v_add_u32_e32 v74, s2, v21
	v_add_u32_e32 v75, s2, v22
	s_mul_i32 s2, s0, 0xc00
	s_add_i32 s2, s2, 0x9ad0800
	v_add_u32_e32 v76, s2, v20
	s_lshl_b32 s2, s0, 9
	s_add_i32 s2, s2, 0xf380800
	v_add_u32_e32 v77, s2, v20
	s_lshl_b32 s2, s0, 4
	s_add_i32 s2, s2, 0xfb90800
	v_add_u32_e32 v78, s2, v23
	s_cmpk_lt_i32 s0, 0x4080
	s_cbranch_scc0 .Lepi_done
	global_load_dwordx2 v[40:41], v72, s[92:93]
	global_load_dwordx2 v[46:47], v74, s[92:93]
	global_load_dwordx2 v[44:45], v73, s[92:93] offset:1536
	global_load_dwordx2 v[42:43], v73, s[92:93] offset:512
	global_load_dwordx2 v[48:49], v75, s[92:93]
	global_load_dword v54, v78, s[92:93]
	global_load_dwordx2 v[50:51], v76, s[92:93] offset:2560
	global_load_dwordx2 v[52:53], v77, s[92:93]
	s_waitcnt vmcnt(0)
	s_mov_b32 s39, 0xbfb8aa3b
	s_mov_b32 s40, 0x3c000000
	s_mov_b32 s41, 0x3c800000
	v_mov_b32_e32 v81, 0x358637bd
	v_mov_b32_e32 v82, 0x3727c5ac
	v_mov_b32_e32 v83, 0x3a27c5ac
.Lepi_loop:
	v_mov_b32_e32 v79, v72
	v_mov_b32_e32 v80, v73
	v_add_u32_e32 v72, s28, v72
	v_add_u32_e32 v73, s28, v73
	v_add_u32_e32 v74, s29, v74
	v_add_u32_e32 v75, s29, v75
	v_add_u32_e32 v76, s30, v76
	v_add_u32_e32 v77, s31, v77
	v_add_u32_e32 v78, s38, v78
	s_add_i32 s0, s0, s1
	s_cmpk_lt_i32 s0, 0x4080
	s_cbranch_scc0 .Lepi_nopfA
	global_load_dwordx2 v[56:57], v72, s[92:93]
	global_load_dwordx2 v[62:63], v74, s[92:93]
	global_load_dwordx2 v[60:61], v73, s[92:93] offset:1536
	global_load_dwordx2 v[58:59], v73, s[92:93] offset:512
	global_load_dwordx2 v[64:65], v75, s[92:93]
	global_load_dword v70, v78, s[92:93]
	global_load_dwordx2 v[66:67], v76, s[92:93] offset:2560
	global_load_dwordx2 v[68:69], v77, s[92:93]
.Lepi_nopfA:
	v_lshlrev_b32_e32 v84, 16, v40
	v_and_b32_e32 v85, 0xffff0000, v40
	v_lshlrev_b32_e32 v86, 16, v41
	v_and_b32_e32 v87, 0xffff0000, v41
	v_lshlrev_b32_e32 v88, 16, v46
	v_and_b32_e32 v89, 0xffff0000, v46
	v_lshlrev_b32_e32 v90, 16, v47
	v_and_b32_e32 v91, 0xffff0000, v47
	v_lshlrev_b32_e32 v92, 16, v44
	v_and_b32_e32 v93, 0xffff0000, v44
	v_lshlrev_b32_e32 v94, 16, v45
	v_and_b32_e32 v95, 0xffff0000, v45
	v_lshlrev_b32_e32 v96, 16, v42
	v_and_b32_e32 v97, 0xffff0000, v42
	v_lshlrev_b32_e32 v98, 16, v43
	v_and_b32_e32 v99, 0xffff0000, v43
	v_lshlrev_b32_e32 v100, 16, v48
	v_and_b32_e32 v101, 0xffff0000, v48
	v_lshlrev_b32_e32 v102, 16, v49
	v_and_b32_e32 v103, 0xffff0000, v49
	v_lshlrev_b32_e32 v104, 16, v50
	v_and_b32_e32 v105, 0xffff0000, v50
	v_lshlrev_b32_e32 v106, 16, v51
	v_and_b32_e32 v107, 0xffff0000, v51
	v_lshlrev_b32_e32 v108, 16, v52
	v_and_b32_e32 v109, 0xffff0000, v52
	v_lshlrev_b32_e32 v110, 16, v53
	v_and_b32_e32 v111, 0xffff0000, v53
	v_mul_f32_e32 v112, s39, v88
	v_mul_f32_e32 v113, s39, v89
	v_mul_f32_e32 v114, s39, v90
	v_mul_f32_e32 v115, s39, v91
	v_exp_f32_e32 v112, v112
	v_exp_f32_e32 v113, v113
	v_exp_f32_e32 v114, v114
	v_exp_f32_e32 v115, v115
	v_add_f32_e32 v112, 1.0, v112
	v_add_f32_e32 v113, 1.0, v113
	v_add_f32_e32 v114, 1.0, v114
	v_add_f32_e32 v115, 1.0, v115
	v_rcp_f32_e32 v112, v112
	v_rcp_f32_e32 v113, v113
	v_rcp_f32_e32 v114, v114
	v_rcp_f32_e32 v115, v115
	v_mul_f32_e32 v112, v88, v112
	v_mul_f32_e32 v113, v89, v113
	v_mul_f32_e32 v114, v90, v114
	v_mul_f32_e32 v115, v91, v115
	v_mul_f32_e32 v116, s39, v100
	v_mul_f32_e32 v117, s39, v101
	v_mul_f32_e32 v118, s39, v102
	v_mul_f32_e32 v119, s39, v103
	v_exp_f32_e32 v116, v116
	v_exp_f32_e32 v117, v117
	v_exp_f32_e32 v118, v118
	v_exp_f32_e32 v119, v119
	v_add_f32_e32 v116, 1.0, v116
	v_add_f32_e32 v117, 1.0, v117
	v_add_f32_e32 v118, 1.0, v118
	v_add_f32_e32 v119, 1.0, v119
	v_rcp_f32_e32 v116, v116
	v_rcp_f32_e32 v117, v117
	v_rcp_f32_e32 v118, v118
	v_rcp_f32_e32 v119, v119
	v_mul_f32_e32 v116, v100, v116
	v_mul_f32_e32 v117, v101, v117
; __device__ __forceinline__ void epi_phase(CP p, int l) {
;     ...
;       float ss = y0 * y0 + y1 * y1 + y2 * y2 + y3 * y3;
; #pragma unroll
;       for (int o = 16; o >= 1; o >>= 1) ss += __shfl_xor(ss, o, 64);
;       const float rs = rsqrtf(ss * (1.f / 128.f) + EPS);
;       uint2 o;
;       o.x = pack2(y0 * rs * nw4.x, y1 * rs * nw4.y);
;       o.y = pack2(y2 * rs * nw4.z, y3 * rs * nw4.w);
;       *reinterpret_cast<uint2*>(Y + (size_t)row * 1024 + c) = o;
;     }
;     {
;       const uint2 yr = *reinterpret_cast<const uint2*>(Y + (size_t)row * 1024 + 768 + c);
;       const uint2 gr = *reinterpret_cast<const uint2*>(proj + (size_t)row * PJ + OFF_RET + 512 + c);
;       const float4 gw = *reinterpret_cast<const float4*>(p.in[32] + l * 256 + c);
;       const float y0 = lo2f(yr.x), y1 = hi2f(yr.x), y2 = lo2f(yr.y), y3 = hi2f(yr.y);
;       float sm = y0 + y1 + y2 + y3;
; #pragma unroll
;       for (int o = 8; o >= 1; o >>= 1) sm += __shfl_xor(sm, o, 64);
;       const float mu = sm * (1.f / 64.f);
;       const float d0 = y0 - mu, d1 = y1 - mu, d2 = y2 - mu, d3 = y3 - mu;
;       float vs = d0 * d0 + d1 * d1 + d2 * d2 + d3 * d3;
; #pragma unroll
;       for (int o = 8; o >= 1; o >>= 1) vs += __shfl_xor(vs, o, 64);
;       const float rs = rsqrtf(vs * (1.f / 64.f) + 1e-5f);
;       uint2 o;
;       o.x = pack2(d0 * rs * gw.x * siluf_(lo2f(gr.x)), d1 * rs * gw.y * siluf_(hi2f(gr.x)));
;       o.y = pack2(d2 * rs * gw.z * siluf_(lo2f(gr.y)), d3 * rs * gw.w * siluf_(hi2f(gr.y)));
;       *reinterpret_cast<uint2*>(Y + (size_t)row * 1024 + 768 + c) = o;
;     }
;     {
;       const uint2 yr = *reinterpret_cast<const uint2*>(Y + (size_t)row * 1024 + 256 + c);
;       const float y0 = lo2f(yr.x), y1 = hi2f(yr.x), y2 = lo2f(yr.y), y3 = hi2f(yr.y);
;       float sm = y0 + y1 + y2 + y3;
; #pragma unroll
;       for (int o = 8; o >= 1; o >>= 1) sm += __shfl_xor(sm, o, 64);
;       const float mu = sm * (1.f / 64.f);
;       const float d0 = y0 - mu, d1 = y1 - mu, d2 = y2 - mu, d3 = y3 - mu;
;       float vs = d0 * d0 + d1 * d1 + d2 * d2 + d3 * d3;
; #pragma unroll
;       for (int o = 8; o >= 1; o >>= 1) vs += __shfl_xor(vs, o, 64);
;       const float rs = rsqrtf(vs * (1.f / 64.f) + 64e-5f);
;       const float coef = RC[(size_t)row * 4 + (lane >> 4)];
;       const uint2 vr = *reinterpret_cast<const uint2*>(RW + (size_t)row * 1536 + 1280 + c);
	v_mul_f32_e32 v118, v102, v118
	v_mul_f32_e32 v119, v103, v119
	v_mul_f32_e32 v84, v84, v112
	v_mul_f32_e32 v85, v85, v113
	v_mul_f32_e32 v86, v86, v114
	v_mul_f32_e32 v87, v87, v115
	v_mul_f32_e32 v120, v84, v84
	v_add_f32_e32 v121, v92, v93
	v_add_f32_e32 v122, v96, v97
	v_fmac_f32_e32 v120, v85, v85
	v_add_f32_e32 v121, v121, v94
	v_add_f32_e32 v122, v122, v98
	v_fmac_f32_e32 v120, v86, v86
	v_add_f32_e32 v121, v121, v95
	v_add_f32_e32 v122, v122, v99
	v_fmac_f32_e32 v120, v87, v87
	s_nop 1
	v_add_f32_dpp v120, v120, v120 quad_perm:[1,0,3,2] row_mask:0xf bank_mask:0xf bound_ctrl:1
	v_add_f32_dpp v121, v121, v121 quad_perm:[1,0,3,2] row_mask:0xf bank_mask:0xf bound_ctrl:1
	v_add_f32_dpp v122, v122, v122 quad_perm:[1,0,3,2] row_mask:0xf bank_mask:0xf bound_ctrl:1
	v_add_f32_dpp v120, v120, v120 quad_perm:[2,3,0,1] row_mask:0xf bank_mask:0xf bound_ctrl:1
	v_add_f32_dpp v121, v121, v121 quad_perm:[2,3,0,1] row_mask:0xf bank_mask:0xf bound_ctrl:1
	v_add_f32_dpp v122, v122, v122 quad_perm:[2,3,0,1] row_mask:0xf bank_mask:0xf bound_ctrl:1
	v_add_f32_dpp v120, v120, v120 row_half_mirror row_mask:0xf bank_mask:0xf bound_ctrl:1
	v_add_f32_dpp v121, v121, v121 row_half_mirror row_mask:0xf bank_mask:0xf bound_ctrl:1
	v_add_f32_dpp v122, v122, v122 row_half_mirror row_mask:0xf bank_mask:0xf bound_ctrl:1
	v_add_f32_dpp v120, v120, v120 row_mirror row_mask:0xf bank_mask:0xf bound_ctrl:1
	v_add_f32_dpp v121, v121, v121 row_mirror row_mask:0xf bank_mask:0xf bound_ctrl:1
	v_add_f32_dpp v122, v122, v122 row_mirror row_mask:0xf bank_mask:0xf bound_ctrl:1
	v_mov_b32_e32 v123, v120
	v_mov_b32_e32 v124, v120
	v_mul_f32_e32 v121, 0xbc800000, v121
	v_mul_f32_e32 v122, 0xbc800000, v122
	v_permlane32_swap_b32_e32 v123, v124
	v_add_f32_e32 v92, v92, v121
	v_add_f32_e32 v93, v93, v121
	v_add_f32_e32 v94, v94, v121
	v_add_f32_e32 v95, v95, v121
	v_add_f32_e32 v96, v96, v122
	v_add_f32_e32 v97, v97, v122
	v_add_f32_e32 v98, v98, v122
	v_add_f32_e32 v99, v99, v122
	v_add_f32_e32 v120, v123, v124
	v_mul_f32_e32 v125, v92, v92
	v_mul_f32_e32 v126, v96, v96
	v_fmac_f32_e32 v125, v93, v93
	v_fmac_f32_e32 v126, v97, v97
	v_fmac_f32_e32 v125, v94, v94
	v_fmac_f32_e32 v126, v98, v98
	v_fmac_f32_e32 v125, v95, v95
	v_fmac_f32_e32 v126, v99, v99
	v_fma_f32 v120, v120, s40, v81
	v_rsq_f32_e32 v120, v120
	v_add_f32_dpp v125, v125, v125 quad_perm:[1,0,3,2] row_mask:0xf bank_mask:0xf bound_ctrl:1
	v_add_f32_dpp v126, v126, v126 quad_perm:[1,0,3,2] row_mask:0xf bank_mask:0xf bound_ctrl:1
	s_nop 0
	v_add_f32_dpp v125, v125, v125 quad_perm:[2,3,0,1] row_mask:0xf bank_mask:0xf bound_ctrl:1
	v_add_f32_dpp v126, v126, v126 quad_perm:[2,3,0,1] row_mask:0xf bank_mask:0xf bound_ctrl:1
	s_nop 0
	v_add_f32_dpp v125, v125, v125 row_half_mirror row_mask:0xf bank_mask:0xf bound_ctrl:1
	v_add_f32_dpp v126, v126, v126 row_half_mirror row_mask:0xf bank_mask:0xf bound_ctrl:1
	s_nop 0
	v_add_f32_dpp v125, v125, v125 row_mirror row_mask:0xf bank_mask:0xf bound_ctrl:1
	v_add_f32_dpp v126, v126, v126 row_mirror row_mask:0xf bank_mask:0xf bound_ctrl:1
	v_mul_f32_e32 v112, v120, v24
	v_mul_f32_e32 v113, v120, v25
	v_mul_f32_e32 v114, v120, v26
	v_mul_f32_e32 v115, v120, v27
	v_mul_f32_e32 v84, v84, v112
	v_mul_f32_e32 v85, v85, v113
	v_mul_f32_e32 v86, v86, v114
	v_mul_f32_e32 v87, v87, v115
	v_fma_f32 v125, v125, s41, v82
	v_fma_f32 v126, v126, s41, v83
	v_cvt_pk_bf16_f32 v84, v84, v85
	v_cvt_pk_bf16_f32 v85, v86, v87
	v_rsq_f32_e32 v125, v125
	v_rsq_f32_e32 v126, v126
	global_store_dwordx2 v79, v[84:85], s[92:93]
	v_mul_f32_e32 v116, v116, v36
	v_mul_f32_e32 v117, v117, v37
	v_mul_f32_e32 v118, v118, v38
	v_mul_f32_e32 v119, v119, v39
	v_mul_f32_e32 v92, v92, v125
	v_mul_f32_e32 v93, v93, v125
	v_mul_f32_e32 v94, v94, v125
	v_mul_f32_e32 v95, v95, v125
	v_mul_f32_e32 v92, v92, v116
	v_mul_f32_e32 v93, v93, v117
	v_mul_f32_e32 v94, v94, v118
	v_mul_f32_e32 v95, v95, v119
	v_mul_f32_e32 v96, v96, v126
	v_mul_f32_e32 v97, v97, v126
	v_mul_f32_e32 v98, v98, v126
	v_mul_f32_e32 v99, v99, v126
	v_fma_f32 v96, v96, v28, v32
	v_fma_f32 v97, v97, v29, v33
	v_fma_f32 v98, v98, v30, v34
	v_fma_f32 v99, v99, v31, v35
	v_fmac_f32_e32 v96, v54, v104
	v_fmac_f32_e32 v97, v54, v105
	v_fmac_f32_e32 v98, v54, v106
	v_fmac_f32_e32 v99, v54, v107
	v_mul_f32_e32 v96, v96, v108
	v_mul_f32_e32 v97, v97, v109
	v_mul_f32_e32 v98, v98, v110
	v_mul_f32_e32 v99, v99, v111
	v_cvt_pk_bf16_f32 v92, v92, v93
	v_cvt_pk_bf16_f32 v93, v94, v95
	v_cvt_pk_bf16_f32 v96, v96, v97
	v_cvt_pk_bf16_f32 v97, v98, v99
	global_store_dwordx2 v80, v[92:93], s[92:93] offset:1536
	global_store_dwordx2 v80, v[96:97], s[92:93] offset:512
	s_waitcnt vmcnt(3)
	s_cmpk_lt_i32 s0, 0x4080
	s_cbranch_scc0 .Lepi_done
	v_mov_b32_e32 v79, v72
	v_mov_b32_e32 v80, v73
	v_add_u32_e32 v72, s28, v72
	v_add_u32_e32 v73, s28, v73
	v_add_u32_e32 v74, s29, v74
	v_add_u32_e32 v75, s29, v75
	v_add_u32_e32 v76, s30, v76
	v_add_u32_e32 v77, s31, v77
	v_add_u32_e32 v78, s38, v78
	s_add_i32 s0, s0, s1
	s_cmpk_lt_i32 s0, 0x4080
	s_cbranch_scc0 .Lepi_nopfB
	global_load_dwordx2 v[40:41], v72, s[92:93]
	global_load_dwordx2 v[46:47], v74, s[92:93]
	global_load_dwordx2 v[44:45], v73, s[92:93] offset:1536
	global_load_dwordx2 v[42:43], v73, s[92:93] offset:512
	global_load_dwordx2 v[48:49], v75, s[92:93]
	global_load_dword v54, v78, s[92:93]
	global_load_dwordx2 v[50:51], v76, s[92:93] offset:2560
	global_load_dwordx2 v[52:53], v77, s[92:93]
; __device__ __forceinline__ void epi_phase(CP p, int l) {
;     ...
;   for (int row = gw; row < R; row += nw) {
;     {
;       const uint2 yr = *reinterpret_cast<const uint2*>(Y + (size_t)row * 1024 + c);
;       const uint2 zr = *reinterpret_cast<const uint2*>(proj + (size_t)row * PJ + OFF_Z + c);
;       const float y0 = lo2f(yr.x) * siluf_(lo2f(zr.x)), y1 = hi2f(yr.x) * siluf_(hi2f(zr.x));
;       const float y2 = lo2f(yr.y) * siluf_(lo2f(zr.y)), y3 = hi2f(yr.y) * siluf_(hi2f(zr.y));
;       float ss = y0 * y0 + y1 * y1 + y2 * y2 + y3 * y3;
; #pragma unroll
;       for (int o = 16; o >= 1; o >>= 1) ss += __shfl_xor(ss, o, 64);
;       const float rs = rsqrtf(ss * (1.f / 128.f) + EPS);
;       uint2 o;
;       o.x = pack2(y0 * rs * nw4.x, y1 * rs * nw4.y);
;       o.y = pack2(y2 * rs * nw4.z, y3 * rs * nw4.w);
;       *reinterpret_cast<uint2*>(Y + (size_t)row * 1024 + c) = o;
;     }
;     {
;       const uint2 yr = *reinterpret_cast<const uint2*>(Y + (size_t)row * 1024 + 768 + c);
;       const uint2 gr = *reinterpret_cast<const uint2*>(proj + (size_t)row * PJ + OFF_RET + 512 + c);
;       const float4 gw = *reinterpret_cast<const float4*>(p.in[32] + l * 256 + c);
;       const float y0 = lo2f(yr.x), y1 = hi2f(yr.x), y2 = lo2f(yr.y), y3 = hi2f(yr.y);
;       float sm = y0 + y1 + y2 + y3;
; #pragma unroll
;       for (int o = 8; o >= 1; o >>= 1) sm += __shfl_xor(sm, o, 64);
;       const float mu = sm * (1.f / 64.f);
;       const float d0 = y0 - mu, d1 = y1 - mu, d2 = y2 - mu, d3 = y3 - mu;
;       float vs = d0 * d0 + d1 * d1 + d2 * d2 + d3 * d3;
; #pragma unroll
;       for (int o = 8; o >= 1; o >>= 1) vs += __shfl_xor(vs, o, 64);
;       const float rs = rsqrtf(vs * (1.f / 64.f) + 1e-5f);
;       uint2 o;
;       o.x = pack2(d0 * rs * gw.x * siluf_(lo2f(gr.x)), d1 * rs * gw.y * siluf_(hi2f(gr.x)));
;       o.y = pack2(d2 * rs * gw.z * siluf_(lo2f(gr.y)), d3 * rs * gw.w * siluf_(hi2f(gr.y)));
;       *reinterpret_cast<uint2*>(Y + (size_t)row * 1024 + 768 + c) = o;
;     }
;     {
;       const uint2 yr = *reinterpret_cast<const uint2*>(Y + (size_t)row * 1024 + 256 + c);
;       const float y0 = lo2f(yr.x), y1 = hi2f(yr.x), y2 = lo2f(yr.y), y3 = hi2f(yr.y);
;       float sm = y0 + y1 + y2 + y3;
; #pragma unroll
;       for (int o = 8; o >= 1; o >>= 1) sm += __shfl_xor(sm, o, 64);
;       const float mu = sm * (1.f / 64.f);
.Lepi_nopfB:
	v_lshlrev_b32_e32 v84, 16, v56
	v_and_b32_e32 v85, 0xffff0000, v56
	v_lshlrev_b32_e32 v86, 16, v57
	v_and_b32_e32 v87, 0xffff0000, v57
	v_lshlrev_b32_e32 v88, 16, v62
	v_and_b32_e32 v89, 0xffff0000, v62
	v_lshlrev_b32_e32 v90, 16, v63
	v_and_b32_e32 v91, 0xffff0000, v63
	v_lshlrev_b32_e32 v92, 16, v60
	v_and_b32_e32 v93, 0xffff0000, v60
	v_lshlrev_b32_e32 v94, 16, v61
	v_and_b32_e32 v95, 0xffff0000, v61
	v_lshlrev_b32_e32 v96, 16, v58
	v_and_b32_e32 v97, 0xffff0000, v58
	v_lshlrev_b32_e32 v98, 16, v59
	v_and_b32_e32 v99, 0xffff0000, v59
	v_lshlrev_b32_e32 v100, 16, v64
	v_and_b32_e32 v101, 0xffff0000, v64
	v_lshlrev_b32_e32 v102, 16, v65
	v_and_b32_e32 v103, 0xffff0000, v65
	v_lshlrev_b32_e32 v104, 16, v66
	v_and_b32_e32 v105, 0xffff0000, v66
	v_lshlrev_b32_e32 v106, 16, v67
	v_and_b32_e32 v107, 0xffff0000, v67
	v_lshlrev_b32_e32 v108, 16, v68
	v_and_b32_e32 v109, 0xffff0000, v68
	v_lshlrev_b32_e32 v110, 16, v69
	v_and_b32_e32 v111, 0xffff0000, v69
	v_mul_f32_e32 v112, s39, v88
	v_mul_f32_e32 v113, s39, v89
	v_mul_f32_e32 v114, s39, v90
	v_mul_f32_e32 v115, s39, v91
	v_exp_f32_e32 v112, v112
	v_exp_f32_e32 v113, v113
	v_exp_f32_e32 v114, v114
	v_exp_f32_e32 v115, v115
	v_add_f32_e32 v112, 1.0, v112
	v_add_f32_e32 v113, 1.0, v113
	v_add_f32_e32 v114, 1.0, v114
	v_add_f32_e32 v115, 1.0, v115
	v_rcp_f32_e32 v112, v112
	v_rcp_f32_e32 v113, v113
	v_rcp_f32_e32 v114, v114
	v_rcp_f32_e32 v115, v115
	v_mul_f32_e32 v112, v88, v112
	v_mul_f32_e32 v113, v89, v113
	v_mul_f32_e32 v114, v90, v114
	v_mul_f32_e32 v115, v91, v115
	v_mul_f32_e32 v116, s39, v100
	v_mul_f32_e32 v117, s39, v101
	v_mul_f32_e32 v118, s39, v102
	v_mul_f32_e32 v119, s39, v103
	v_exp_f32_e32 v116, v116
	v_exp_f32_e32 v117, v117
	v_exp_f32_e32 v118, v118
	v_exp_f32_e32 v119, v119
	v_add_f32_e32 v116, 1.0, v116
	v_add_f32_e32 v117, 1.0, v117
	v_add_f32_e32 v118, 1.0, v118
	v_add_f32_e32 v119, 1.0, v119
	v_rcp_f32_e32 v116, v116
	v_rcp_f32_e32 v117, v117
	v_rcp_f32_e32 v118, v118
	v_rcp_f32_e32 v119, v119
	v_mul_f32_e32 v116, v100, v116
	v_mul_f32_e32 v117, v101, v117
	v_mul_f32_e32 v118, v102, v118
	v_mul_f32_e32 v119, v103, v119
	v_mul_f32_e32 v84, v84, v112
	v_mul_f32_e32 v85, v85, v113
	v_mul_f32_e32 v86, v86, v114
	v_mul_f32_e32 v87, v87, v115
	v_mul_f32_e32 v120, v84, v84
	v_add_f32_e32 v121, v92, v93
	v_add_f32_e32 v122, v96, v97
	v_fmac_f32_e32 v120, v85, v85
	v_add_f32_e32 v121, v121, v94
	v_add_f32_e32 v122, v122, v98
	v_fmac_f32_e32 v120, v86, v86
	v_add_f32_e32 v121, v121, v95
	v_add_f32_e32 v122, v122, v99
	v_fmac_f32_e32 v120, v87, v87
	s_nop 1
	v_add_f32_dpp v120, v120, v120 quad_perm:[1,0,3,2] row_mask:0xf bank_mask:0xf bound_ctrl:1
	v_add_f32_dpp v121, v121, v121 quad_perm:[1,0,3,2] row_mask:0xf bank_mask:0xf bound_ctrl:1
	v_add_f32_dpp v122, v122, v122 quad_perm:[1,0,3,2] row_mask:0xf bank_mask:0xf bound_ctrl:1
	v_add_f32_dpp v120, v120, v120 quad_perm:[2,3,0,1] row_mask:0xf bank_mask:0xf bound_ctrl:1
	v_add_f32_dpp v121, v121, v121 quad_perm:[2,3,0,1] row_mask:0xf bank_mask:0xf bound_ctrl:1
	v_add_f32_dpp v122, v122, v122 quad_perm:[2,3,0,1] row_mask:0xf bank_mask:0xf bound_ctrl:1
	v_add_f32_dpp v120, v120, v120 row_half_mirror row_mask:0xf bank_mask:0xf bound_ctrl:1
	v_add_f32_dpp v121, v121, v121 row_half_mirror row_mask:0xf bank_mask:0xf bound_ctrl:1
	v_add_f32_dpp v122, v122, v122 row_half_mirror row_mask:0xf bank_mask:0xf bound_ctrl:1
	v_add_f32_dpp v120, v120, v120 row_mirror row_mask:0xf bank_mask:0xf bound_ctrl:1
	v_add_f32_dpp v121, v121, v121 row_mirror row_mask:0xf bank_mask:0xf bound_ctrl:1
	v_add_f32_dpp v122, v122, v122 row_mirror row_mask:0xf bank_mask:0xf bound_ctrl:1
	v_mov_b32_e32 v123, v120
	v_mov_b32_e32 v124, v120
	v_mul_f32_e32 v121, 0xbc800000, v121
	v_mul_f32_e32 v122, 0xbc800000, v122
	v_permlane32_swap_b32_e32 v123, v124
	v_add_f32_e32 v92, v92, v121
	v_add_f32_e32 v93, v93, v121
	v_add_f32_e32 v94, v94, v121
	v_add_f32_e32 v95, v95, v121
	v_add_f32_e32 v96, v96, v122
	v_add_f32_e32 v97, v97, v122
	v_add_f32_e32 v98, v98, v122
	v_add_f32_e32 v99, v99, v122
	v_add_f32_e32 v120, v123, v124
	v_mul_f32_e32 v125, v92, v92
	v_mul_f32_e32 v126, v96, v96
	v_fmac_f32_e32 v125, v93, v93
	v_fmac_f32_e32 v126, v97, v97
	v_fmac_f32_e32 v125, v94, v94
	v_fmac_f32_e32 v126, v98, v98
	v_fmac_f32_e32 v125, v95, v95
	v_fmac_f32_e32 v126, v99, v99
	v_fma_f32 v120, v120, s40, v81
	v_rsq_f32_e32 v120, v120
	v_add_f32_dpp v125, v125, v125 quad_perm:[1,0,3,2] row_mask:0xf bank_mask:0xf bound_ctrl:1
	v_add_f32_dpp v126, v126, v126 quad_perm:[1,0,3,2] row_mask:0xf bank_mask:0xf bound_ctrl:1
	s_nop 0
	v_add_f32_dpp v125, v125, v125 quad_perm:[2,3,0,1] row_mask:0xf bank_mask:0xf bound_ctrl:1
	v_add_f32_dpp v126, v126, v126 quad_perm:[2,3,0,1] row_mask:0xf bank_mask:0xf bound_ctrl:1
	s_nop 0
	v_add_f32_dpp v125, v125, v125 row_half_mirror row_mask:0xf bank_mask:0xf bound_ctrl:1
	v_add_f32_dpp v126, v126, v126 row_half_mirror row_mask:0xf bank_mask:0xf bound_ctrl:1
	s_nop 0
	v_add_f32_dpp v125, v125, v125 row_mirror row_mask:0xf bank_mask:0xf bound_ctrl:1
	v_add_f32_dpp v126, v126, v126 row_mirror row_mask:0xf bank_mask:0xf bound_ctrl:1
	v_mul_f32_e32 v112, v120, v24
	v_mul_f32_e32 v113, v120, v25
	v_mul_f32_e32 v114, v120, v26
	v_mul_f32_e32 v115, v120, v27
	v_mul_f32_e32 v84, v84, v112
	v_mul_f32_e32 v85, v85, v113
	v_mul_f32_e32 v86, v86, v114
	v_mul_f32_e32 v87, v87, v115
	v_fma_f32 v125, v125, s41, v82
	v_fma_f32 v126, v126, s41, v83
	v_cvt_pk_bf16_f32 v84, v84, v85
	v_cvt_pk_bf16_f32 v85, v86, v87
	v_rsq_f32_e32 v125, v125
	v_rsq_f32_e32 v126, v126
	global_store_dwordx2 v79, v[84:85], s[92:93]
	v_mul_f32_e32 v116, v116, v36
	v_mul_f32_e32 v117, v117, v37
	v_mul_f32_e32 v118, v118, v38
	v_mul_f32_e32 v119, v119, v39
	v_mul_f32_e32 v92, v92, v125
	v_mul_f32_e32 v93, v93, v125
	v_mul_f32_e32 v94, v94, v125
	v_mul_f32_e32 v95, v95, v125
	v_mul_f32_e32 v92, v92, v116
	v_mul_f32_e32 v93, v93, v117
	v_mul_f32_e32 v94, v94, v118
	v_mul_f32_e32 v95, v95, v119
	v_mul_f32_e32 v96, v96, v126
	v_mul_f32_e32 v97, v97, v126
	v_mul_f32_e32 v98, v98, v126
	v_mul_f32_e32 v99, v99, v126
	v_fma_f32 v96, v96, v28, v32
	v_fma_f32 v97, v97, v29, v33
	v_fma_f32 v98, v98, v30, v34
	v_fma_f32 v99, v99, v31, v35
	v_fmac_f32_e32 v96, v70, v104
	v_fmac_f32_e32 v97, v70, v105
	v_fmac_f32_e32 v98, v70, v106
	v_fmac_f32_e32 v99, v70, v107
	v_mul_f32_e32 v96, v96, v108
	v_mul_f32_e32 v97, v97, v109
	v_mul_f32_e32 v98, v98, v110
	v_mul_f32_e32 v99, v99, v111
	v_cvt_pk_bf16_f32 v92, v92, v93
	v_cvt_pk_bf16_f32 v93, v94, v95
	v_cvt_pk_bf16_f32 v96, v96, v97
	v_cvt_pk_bf16_f32 v97, v98, v99
	global_store_dwordx2 v80, v[92:93], s[92:93] offset:1536
	global_store_dwordx2 v80, v[96:97], s[92:93] offset:512
	s_waitcnt vmcnt(3)
	s_cmpk_lt_i32 s0, 0x4080
	s_cbranch_scc1 .Lepi_loop
.Lepi_done:
	s_branch .LBB0_649
